# queue item claimed during a scan's last chunk (returning atomic parked in v255), consumed at the dispatcher
# speedup vs baseline: 1.0489x; 1.0043x over previous
.LBB0_226:
	v_writelane_b32 v254, s28, 36
	s_nop 1
	v_writelane_b32 v254, s29, 37
	v_writelane_b32 v254, s26, 38
	s_nop 1
	v_writelane_b32 v254, s27, 39
	v_writelane_b32 v254, s99, 40
	s_or_b64 exec, exec, s[0:1]
	s_cmpk_gt_i32 s2, 0x7f
	s_cselect_b64 s[0:1], -1, 0
	s_and_b32 s10, s2, 7
	s_ashr_i32 s97, s2, 3
	s_lshl_b32 s3, s10, 6
	s_lshl_b32 s4, s10, 8
	s_add_u32 s4, s88, s4
	s_addc_u32 s5, s89, 0
	s_add_u32 s8, s4, 0x3700
	s_addc_u32 s9, s5, 0
	s_lshl_b32 s6, s10, 4
	s_or_b32 s13, s6, s97
	s_cmp_gt_i32 s2, 63
	s_movk_i32 s2, 0x80
	s_cselect_b32 s2, s2, 0x110
	v_writelane_b32 v254, s2, 41
	s_movk_i32 s2, 0x80
	s_cselect_b32 s7, s2, 0x90
	s_cselect_b32 s14, 0x90, s2
	s_add_u32 s16, s8, s7
	v_writelane_b32 v254, s8, 34
	s_addc_u32 s17, s9, 0
	s_add_i32 s2, s6, 64
	v_writelane_b32 v254, s9, 35
	v_writelane_b32 v254, s2, 42
	v_writelane_b32 v254, s10, 43
	s_lshl_b32 s2, s10, 3
	v_writelane_b32 v254, s2, 44
	s_add_i32 s2, s3, 0x80
	v_writelane_b32 v254, s2, 45
	s_add_u32 s2, s4, 0x37a0
	s_addc_u32 s3, s5, 0
	v_writelane_b32 v254, s2, 46
	s_mov_b32 s77, 0
	v_mov_b32_e32 v3, 0
	v_writelane_b32 v254, s3, 47
	s_add_u32 s2, s42, 0x1000
	s_addc_u32 s3, s43, 0
	v_writelane_b32 v254, s2, 48
	s_add_i32 s15, 16, 0x11604
	s_add_i32 s18, 16, 0x11600
	v_writelane_b32 v254, s3, 49
	v_writelane_b32 v254, s13, 50
	v_writelane_b32 v254, s14, 51
	v_writelane_b32 v254, s16, 52
	s_movk_i32 s29, 0x1840
	s_movk_i32 s30, 0x70
	v_writelane_b32 v254, s17, 53
	s_mov_b64 s[98:99], 0x30800
	s_add_i32 s31, 16, 0x11000
	s_mov_b32 s33, 0x5040100
	s_mov_b32 s72, 0x7060302
	s_mov_b32 s73, 0xbfb8aa3b
	s_mov_b32 s66, 0x800000
	s_mov_b32 s67, 0x3f317217
	s_mov_b32 s70, 0x7f800000
	s_mov_b32 s96, 0x3d800000
	v_mov_b32_e32 v106, 2.0
	s_movk_i32 s19, 0xc20
	v_mov_b32_e32 v136, s18
	v_mov_b32_e32 v137, 0x61000
	v_mov_b32_e32 v138, 0x41b17218
	v_mbcnt_hi_u32_b32 v1, -1, v1
	v_writelane_b32 v254, s15, 54
	s_waitcnt lgkmcnt(0)
	s_barrier
	v_mov_b32_e32 v255, -1
	v_writelane_b32 v254, s18, 55
	s_branch .LBB0_230

.LBB0_233:
	v_cmp_ne_u32_e32 vcc, 0, v4
	v_mov_b32_e32 v5, s15
	ds_write_b32 v5, v4
	s_cbranch_vccnz .LBB0_237
	v_cmp_ne_u32_e32 vcc, -1, v255
	s_cbranch_vccz .Lqp_nopref
	s_waitcnt vmcnt(0)
	v_mov_b32_e32 v2, v255
	v_mov_b32_e32 v255, -1
	s_branch .LBB0_237
.Lqp_nopref:
	s_mov_b64 s[6:7], exec
	v_mbcnt_lo_u32_b32 v2, s6, 0
	v_mbcnt_hi_u32_b32 v2, s7, v2
	v_cmp_eq_u32_e32 vcc, 0, v2
	s_and_saveexec_b64 s[4:5], vcc
	s_cbranch_execz .LBB0_236
	s_bcnt1_i32_b64 s6, s[6:7]
	v_mov_b32_e32 v4, s6
	v_readlane_b32 s6, v254, 34
	v_readlane_b32 s7, v254, 35
	s_nop 4
	global_atomic_add v4, v3, v4, s[6:7] offset:64 sc0

.LBB0_304:
	s_mov_b32 s0, s38
	s_add_i32 s56, s56, 1
	s_add_i32 s38, s38, s39
	s_cmp_lt_u32 s56, s71
	s_cselect_b32 s58, s38, s0
	s_waitcnt vmcnt(4)
	s_cmp_lg_u32 s56, s71
	s_cbranch_scc1 .Lqp_skip
	v_readlane_b32 s60, v254, 34
	v_readlane_b32 s61, v254, 35
	v_mov_b32_e32 v231, 1
	s_nop 1
	v_mov_b32_e32 v232, s60
	v_mov_b32_e32 v233, s61
	v_cmp_eq_u32_e32 vcc, 0, v0
	s_and_saveexec_b64 s[60:61], vcc
	global_atomic_add v255, v[232:233], v231, off offset:64 sc0
	s_or_b64 exec, exec, s[60:61]
.Lqp_skip:
	v_mad_i64_i32 v[54:55], s[0:1], s58, v137, v[4:5]
	s_mov_b32 s69, s77
	v_lshl_add_u64 v[56:57], v[54:55], 0, s[76:77]
	v_lshl_add_u64 v[58:59], v[54:55], 0, s[68:69]
	v_lshl_add_u64 v[54:55], v[54:55], 0, s[98:99]
	global_load_dwordx4 v[86:89], v[56:57], off
	global_load_dwordx4 v[82:85], v[58:59], off
	v_lshl_add_u64 v[56:57], v[54:55], 0, s[76:77]
	v_lshl_add_u64 v[54:55], v[54:55], 0, s[68:69]
	global_load_dwordx4 v[78:81], v[56:57], off
	global_load_dwordx4 v[74:77], v[54:55], off
	v_mad_i64_i32 v[54:55], s[0:1], s58, v137, v[112:113]
	v_add_co_u32_e32 v56, vcc, 0x1000, v54
	s_nop 1
	v_addc_co_u32_e32 v57, vcc, 0, v55, vcc
	global_load_dwordx4 v[66:69], v[54:55], off
	global_load_dwordx4 v[58:61], v[54:55], off offset:128
	global_load_dwordx4 v[70:73], v[56:57], off offset:2112
	global_load_dwordx4 v[62:65], v[56:57], off offset:2240
	v_mad_i64_i32 v[54:55], s[0:1], s58, v137, v[114:115]
	global_load_dwordx4 v[54:57], v[54:55], off
	s_and_b64 vcc, exec, s[4:5]
	s_cbranch_vccnz .LBB0_314
	v_add3_u32 v98, v107, v186, 16
	v_add3_u32 v99, v107, v187, 16
	v_add3_u32 v100, v107, v190, 16
	v_add3_u32 v101, v107, v191, 16
	v_add3_u32 v102, v107, v194, 16
	v_add3_u32 v103, v107, v195, 16
	v_add3_u32 v104, v107, v198, 16
	v_add3_u32 v105, v107, v199, 16
	ds_read2st64_b32 v[220:221], v165 offset1:1
	ds_read2st64_b32 v[222:223], v165 offset0:2 offset1:3
	ds_read_u16 v236, v98
	ds_read_u16 v237, v98 offset:8192
	ds_read_u16 v238, v98 offset:128
	ds_read_u16 v239, v98 offset:8320
	ds_read_u16 v240, v99 offset:256
	ds_read_u16 v241, v99 offset:8448
	ds_read_u16 v242, v99 offset:384
	ds_read_u16 v243, v99 offset:8576
	s_waitcnt lgkmcnt(0)
	ds_read2st64_b32 v[224:225], v188 offset1:1
	ds_read2st64_b32 v[226:227], v188 offset0:2 offset1:3
	ds_read_u16 v244, v100
	ds_read_u16 v245, v100 offset:8192
	ds_read_u16 v246, v100 offset:128
	ds_read_u16 v247, v100 offset:8320
	ds_read_u16 v248, v101 offset:256
	ds_read_u16 v249, v101 offset:8448
	ds_read_u16 v250, v101 offset:384
	ds_read_u16 v251, v101 offset:8576
	v_add_f32_e32 v2, v220, v221
	v_add_f32_e32 v2, v2, v222
	v_add_f32_e32 v253, v2, v223
	v_mul_f32_e32 v223, 0x3fb8aa3b, v253
	v_exp_f32_e32 v223, v223
	v_cndmask_b32_e64 v2, 0, v220, s[18:19]
	v_cndmask_b32_e64 v220, 0, v221, s[14:15]
	v_add_f32_e32 v2, v2, v220
	v_cndmask_b32_e64 v220, 0, v222, s[20:21]
	v_add_f32_e32 v2, v2, v220
	v_add_f32_e32 v220, v95, v2
	v_sub_f32_e32 v221, v253, v220
	v_add_f32_e32 v2, v91, v220
	v_cndmask_b32_e64 v95, v221, v2, s[2:3]
	v_sub_f32_e32 v2, v221, v91
	v_add_f32_e32 v253, v94, v220
	v_cndmask_b32_e64 v91, v2, v253, s[2:3]
	v_sub_f32_e32 v2, v221, v94
	v_add_f32_e32 v253, v93, v220
	v_cndmask_b32_e64 v94, v2, v253, s[2:3]
	v_sub_f32_e32 v2, v221, v93
	v_add_f32_e32 v253, v92, v220
	v_cndmask_b32_e64 v93, v2, v253, s[2:3]
	v_mul_f32_e32 v95, 0x3fb8aa3b, v95
	v_mul_f32_e32 v91, 0x3fb8aa3b, v91
	v_mul_f32_e32 v94, 0x3fb8aa3b, v94
	v_mul_f32_e32 v93, 0x3fb8aa3b, v93
	v_exp_f32_e32 v95, v95
	v_exp_f32_e32 v91, v91
	v_exp_f32_e32 v94, v94
	v_exp_f32_e32 v93, v93
	v_rcp_f32_e32 v92, v95
	v_rcp_f32_e32 v220, v91
	v_rcp_f32_e32 v221, v94
	v_rcp_f32_e32 v222, v93
	s_waitcnt lgkmcnt(0)
	s_and_saveexec_b64 s[0:1], s[82:83]
	ds_write_b32 v185, v223
	s_or_b64 exec, exec, s[0:1]
	v_lshlrev_b32_e32 v2, 16, v236
	v_lshlrev_b32_e32 v253, 16, v237
	v_mul_f32_e32 v2, v95, v2
	v_mul_f32_e32 v253, v92, v253
	v_cvt_pk_bf16_f32 v236, v2, v253
	ds_write_b16 v98, v236
	ds_write_b16_d16_hi v98, v236 offset:8192
	v_mul_f32_e32 v95, v223, v253
	v_lshlrev_b32_e32 v2, 16, v238
	v_lshlrev_b32_e32 v253, 16, v239
	v_mul_f32_e32 v2, v91, v2
	v_mul_f32_e32 v253, v220, v253
	v_cvt_pk_bf16_f32 v238, v2, v253
	ds_write_b16 v98, v238 offset:128
	ds_write_b16_d16_hi v98, v238 offset:8320
	v_mul_f32_e32 v91, v223, v253
	v_lshlrev_b32_e32 v2, 16, v240
	v_lshlrev_b32_e32 v253, 16, v241
	v_mul_f32_e32 v2, v94, v2
	v_mul_f32_e32 v253, v221, v253
	v_cvt_pk_bf16_f32 v240, v2, v253
	ds_write_b16 v99, v240 offset:256
	ds_write_b16_d16_hi v99, v240 offset:8448
	v_mul_f32_e32 v94, v223, v253
	v_lshlrev_b32_e32 v2, 16, v242
	v_lshlrev_b32_e32 v253, 16, v243
	v_mul_f32_e32 v2, v93, v2
	v_mul_f32_e32 v253, v222, v253
	v_cvt_pk_bf16_f32 v242, v2, v253
	ds_write_b16 v99, v242 offset:384
	ds_write_b16_d16_hi v99, v242 offset:8576
	v_mul_f32_e32 v93, v223, v253
	v_cvt_pk_bf16_f32 v236, v95, v91
	v_cvt_pk_bf16_f32 v237, v94, v93
	v_add_u32_e32 v252, v182, v144
	ds_write_b64 v252, v[236:237] offset:16384
	s_waitcnt lgkmcnt(5)
	ds_read2st64_b32 v[228:229], v192 offset1:1
	ds_read2st64_b32 v[230:231], v192 offset0:2 offset1:3
	ds_read_u16 v236, v102
	ds_read_u16 v237, v102 offset:8192
	ds_read_u16 v238, v102 offset:128
	ds_read_u16 v239, v102 offset:8320
	ds_read_u16 v240, v103 offset:256
	ds_read_u16 v241, v103 offset:8448
	ds_read_u16 v242, v103 offset:384
	ds_read_u16 v243, v103 offset:8576
	v_add_f32_e32 v2, v224, v225
	v_add_f32_e32 v2, v2, v226
	v_add_f32_e32 v253, v2, v227
	v_mul_f32_e32 v227, 0x3fb8aa3b, v253
	v_exp_f32_e32 v227, v227
	v_cndmask_b32_e64 v2, 0, v224, s[18:19]
	v_cndmask_b32_e64 v224, 0, v225, s[14:15]
	v_add_f32_e32 v2, v2, v224
	v_cndmask_b32_e64 v224, 0, v226, s[20:21]
	v_add_f32_e32 v2, v2, v224
	v_add_f32_e32 v224, v211, v2
	v_sub_f32_e32 v225, v253, v224
	v_add_f32_e32 v2, v90, v224
	v_cndmask_b32_e64 v211, v225, v2, s[2:3]
	v_sub_f32_e32 v2, v225, v90
	v_add_f32_e32 v253, v210, v224
	v_cndmask_b32_e64 v90, v2, v253, s[2:3]
	v_sub_f32_e32 v2, v225, v210
	v_add_f32_e32 v253, v135, v224
	v_cndmask_b32_e64 v210, v2, v253, s[2:3]
	v_sub_f32_e32 v2, v225, v135
	v_add_f32_e32 v253, v209, v224
	v_cndmask_b32_e64 v135, v2, v253, s[2:3]
	v_mul_f32_e32 v211, 0x3fb8aa3b, v211
	v_mul_f32_e32 v90, 0x3fb8aa3b, v90
	v_mul_f32_e32 v210, 0x3fb8aa3b, v210
	v_mul_f32_e32 v135, 0x3fb8aa3b, v135
	v_exp_f32_e32 v211, v211
	v_exp_f32_e32 v90, v90
	v_exp_f32_e32 v210, v210
	v_exp_f32_e32 v135, v135
	v_rcp_f32_e32 v209, v211
	v_rcp_f32_e32 v224, v90
	v_rcp_f32_e32 v225, v210
	v_rcp_f32_e32 v226, v135
	s_waitcnt lgkmcnt(0)
	s_and_saveexec_b64 s[0:1], s[82:83]
	ds_write_b32 v189, v227
	s_or_b64 exec, exec, s[0:1]
	v_lshlrev_b32_e32 v2, 16, v244
	v_lshlrev_b32_e32 v253, 16, v245
	v_mul_f32_e32 v2, v211, v2
	v_mul_f32_e32 v253, v209, v253
	v_cvt_pk_bf16_f32 v244, v2, v253
	ds_write_b16 v100, v244
	ds_write_b16_d16_hi v100, v244 offset:8192
	v_mul_f32_e32 v211, v227, v253
	v_lshlrev_b32_e32 v2, 16, v246
	v_lshlrev_b32_e32 v253, 16, v247
	v_mul_f32_e32 v2, v90, v2
	v_mul_f32_e32 v253, v224, v253
	v_cvt_pk_bf16_f32 v246, v2, v253
	ds_write_b16 v100, v246 offset:128
	ds_write_b16_d16_hi v100, v246 offset:8320
	v_mul_f32_e32 v90, v227, v253
	v_lshlrev_b32_e32 v2, 16, v248
	v_lshlrev_b32_e32 v253, 16, v249
	v_mul_f32_e32 v2, v210, v2
	v_mul_f32_e32 v253, v225, v253
	v_cvt_pk_bf16_f32 v248, v2, v253
	ds_write_b16 v101, v248 offset:256
	ds_write_b16_d16_hi v101, v248 offset:8448
	v_mul_f32_e32 v210, v227, v253
	v_lshlrev_b32_e32 v2, 16, v250
	v_lshlrev_b32_e32 v253, 16, v251
	v_mul_f32_e32 v2, v135, v2
	v_mul_f32_e32 v253, v226, v253
	v_cvt_pk_bf16_f32 v250, v2, v253
	ds_write_b16 v101, v250 offset:384
	ds_write_b16_d16_hi v101, v250 offset:8576
	v_mul_f32_e32 v135, v227, v253
	v_cvt_pk_bf16_f32 v244, v211, v90
	v_cvt_pk_bf16_f32 v245, v210, v135
	ds_write_b64 v203, v[244:245] offset:16384
	s_waitcnt lgkmcnt(5)
	ds_read2st64_b32 v[232:233], v196 offset1:1
	ds_read2st64_b32 v[234:235], v196 offset0:2 offset1:3
	ds_read_u16 v244, v104
	ds_read_u16 v245, v104 offset:8192
	ds_read_u16 v246, v104 offset:128
	ds_read_u16 v247, v104 offset:8320
	ds_read_u16 v248, v105 offset:256
	ds_read_u16 v249, v105 offset:8448
	ds_read_u16 v250, v105 offset:384
	ds_read_u16 v251, v105 offset:8576
	v_add_f32_e32 v2, v228, v229
	v_add_f32_e32 v2, v2, v230
	v_add_f32_e32 v253, v2, v231
	v_mul_f32_e32 v231, 0x3fb8aa3b, v253
	v_exp_f32_e32 v231, v231
	v_cndmask_b32_e64 v2, 0, v228, s[18:19]
	v_cndmask_b32_e64 v228, 0, v229, s[14:15]
	v_add_f32_e32 v2, v2, v228
	v_cndmask_b32_e64 v228, 0, v230, s[20:21]
	v_add_f32_e32 v2, v2, v228
	v_add_f32_e32 v228, v215, v2
	v_sub_f32_e32 v229, v253, v228
	v_add_f32_e32 v2, v97, v228
	v_cndmask_b32_e64 v215, v229, v2, s[2:3]
	v_sub_f32_e32 v2, v229, v97
	v_add_f32_e32 v253, v214, v228
	v_cndmask_b32_e64 v97, v2, v253, s[2:3]
	v_sub_f32_e32 v2, v229, v214
	v_add_f32_e32 v253, v212, v228
	v_cndmask_b32_e64 v214, v2, v253, s[2:3]
	v_sub_f32_e32 v2, v229, v212
	v_add_f32_e32 v253, v213, v228
	v_cndmask_b32_e64 v212, v2, v253, s[2:3]
	v_mul_f32_e32 v215, 0x3fb8aa3b, v215
	v_mul_f32_e32 v97, 0x3fb8aa3b, v97
	v_mul_f32_e32 v214, 0x3fb8aa3b, v214
	v_mul_f32_e32 v212, 0x3fb8aa3b, v212
	v_exp_f32_e32 v215, v215
	v_exp_f32_e32 v97, v97
	v_exp_f32_e32 v214, v214
	v_exp_f32_e32 v212, v212
	v_rcp_f32_e32 v213, v215
	v_rcp_f32_e32 v228, v97
	v_rcp_f32_e32 v229, v214
	v_rcp_f32_e32 v230, v212
	s_waitcnt lgkmcnt(0)
	s_and_saveexec_b64 s[0:1], s[82:83]
	ds_write_b32 v193, v231
	s_or_b64 exec, exec, s[0:1]
	v_lshlrev_b32_e32 v2, 16, v236
	v_lshlrev_b32_e32 v253, 16, v237
	v_mul_f32_e32 v2, v215, v2
	v_mul_f32_e32 v253, v213, v253
	v_cvt_pk_bf16_f32 v236, v2, v253
	ds_write_b16 v102, v236
	ds_write_b16_d16_hi v102, v236 offset:8192
	v_mul_f32_e32 v215, v231, v253
	v_lshlrev_b32_e32 v2, 16, v238
	v_lshlrev_b32_e32 v253, 16, v239
	v_mul_f32_e32 v2, v97, v2
	v_mul_f32_e32 v253, v228, v253
	v_cvt_pk_bf16_f32 v238, v2, v253
	ds_write_b16 v102, v238 offset:128
	ds_write_b16_d16_hi v102, v238 offset:8320
	v_mul_f32_e32 v97, v231, v253
	v_lshlrev_b32_e32 v2, 16, v240
	v_lshlrev_b32_e32 v253, 16, v241
	v_mul_f32_e32 v2, v214, v2
	v_mul_f32_e32 v253, v229, v253
	v_cvt_pk_bf16_f32 v240, v2, v253
	ds_write_b16 v103, v240 offset:256
	ds_write_b16_d16_hi v103, v240 offset:8448
	v_mul_f32_e32 v214, v231, v253
	v_lshlrev_b32_e32 v2, 16, v242
	v_lshlrev_b32_e32 v253, 16, v243
	v_mul_f32_e32 v2, v212, v2
	v_mul_f32_e32 v253, v230, v253
	v_cvt_pk_bf16_f32 v242, v2, v253
	ds_write_b16 v103, v242 offset:384
	ds_write_b16_d16_hi v103, v242 offset:8576
	v_mul_f32_e32 v212, v231, v253
	v_cvt_pk_bf16_f32 v236, v215, v97
	v_cvt_pk_bf16_f32 v237, v214, v212
	ds_write_b64 v204, v[236:237] offset:16384
	v_add_f32_e32 v2, v232, v233
	v_add_f32_e32 v2, v2, v234
	v_add_f32_e32 v253, v2, v235
	v_mul_f32_e32 v235, 0x3fb8aa3b, v253
	v_exp_f32_e32 v235, v235
	v_cndmask_b32_e64 v2, 0, v232, s[18:19]
	v_cndmask_b32_e64 v232, 0, v233, s[14:15]
	v_add_f32_e32 v2, v2, v232
	v_cndmask_b32_e64 v232, 0, v234, s[20:21]
	v_add_f32_e32 v2, v2, v232
	v_add_f32_e32 v232, v219, v2
	v_sub_f32_e32 v233, v253, v232
	v_add_f32_e32 v2, v96, v232
	v_cndmask_b32_e64 v219, v233, v2, s[2:3]
	v_sub_f32_e32 v2, v233, v96
	v_add_f32_e32 v253, v218, v232
	v_cndmask_b32_e64 v96, v2, v253, s[2:3]
	v_sub_f32_e32 v2, v233, v218
	v_add_f32_e32 v253, v216, v232
	v_cndmask_b32_e64 v218, v2, v253, s[2:3]
	v_sub_f32_e32 v2, v233, v216
	v_add_f32_e32 v253, v217, v232
	v_cndmask_b32_e64 v216, v2, v253, s[2:3]
	v_mul_f32_e32 v219, 0x3fb8aa3b, v219
	v_mul_f32_e32 v96, 0x3fb8aa3b, v96
	v_mul_f32_e32 v218, 0x3fb8aa3b, v218
	v_mul_f32_e32 v216, 0x3fb8aa3b, v216
	v_exp_f32_e32 v219, v219
	v_exp_f32_e32 v96, v96
	v_exp_f32_e32 v218, v218
	v_exp_f32_e32 v216, v216
	v_rcp_f32_e32 v217, v219
	v_rcp_f32_e32 v232, v96
	v_rcp_f32_e32 v233, v218
	v_rcp_f32_e32 v234, v216
	s_waitcnt lgkmcnt(0)
	s_and_saveexec_b64 s[0:1], s[82:83]
	ds_write_b32 v197, v235
	s_or_b64 exec, exec, s[0:1]
	v_lshlrev_b32_e32 v2, 16, v244
	v_lshlrev_b32_e32 v253, 16, v245
	v_mul_f32_e32 v2, v219, v2
	v_mul_f32_e32 v253, v217, v253
	v_cvt_pk_bf16_f32 v244, v2, v253
	ds_write_b16 v104, v244
	ds_write_b16_d16_hi v104, v244 offset:8192
	v_mul_f32_e32 v219, v235, v253
	v_lshlrev_b32_e32 v2, 16, v246
	v_lshlrev_b32_e32 v253, 16, v247
	v_mul_f32_e32 v2, v96, v2
	v_mul_f32_e32 v253, v232, v253
	v_cvt_pk_bf16_f32 v246, v2, v253
	ds_write_b16 v104, v246 offset:128
	ds_write_b16_d16_hi v104, v246 offset:8320
	v_mul_f32_e32 v96, v235, v253
	v_lshlrev_b32_e32 v2, 16, v248
	v_lshlrev_b32_e32 v253, 16, v249
	v_mul_f32_e32 v2, v218, v2
	v_mul_f32_e32 v253, v233, v253
	v_cvt_pk_bf16_f32 v248, v2, v253
	ds_write_b16 v105, v248 offset:256
	ds_write_b16_d16_hi v105, v248 offset:8448
	v_mul_f32_e32 v218, v235, v253
	v_lshlrev_b32_e32 v2, 16, v250
	v_lshlrev_b32_e32 v253, 16, v251
	v_mul_f32_e32 v2, v216, v2
	v_mul_f32_e32 v253, v234, v253
	v_cvt_pk_bf16_f32 v250, v2, v253
	ds_write_b16 v105, v250 offset:384
	ds_write_b16_d16_hi v105, v250 offset:8576
	v_mul_f32_e32 v216, v235, v253
	v_cvt_pk_bf16_f32 v244, v219, v96
	v_cvt_pk_bf16_f32 v245, v218, v216
	ds_write_b64 v205, v[244:245] offset:16384
	s_waitcnt lgkmcnt(0)
	s_barrier

	.amdhsa_kernel _Z11mega_kernel1P
		.amdhsa_group_segment_fixed_size 16
		.amdhsa_private_segment_fixed_size 0
		.amdhsa_kernarg_size 480
		.amdhsa_user_sgpr_count 2
		.amdhsa_user_sgpr_dispatch_ptr 0
		.amdhsa_user_sgpr_queue_ptr 0
		.amdhsa_user_sgpr_kernarg_segment_ptr 1
		.amdhsa_user_sgpr_dispatch_id 0
		.amdhsa_user_sgpr_kernarg_preload_length 0
		.amdhsa_user_sgpr_kernarg_preload_offset 0
		.amdhsa_user_sgpr_private_segment_size 0
		.amdhsa_uses_dynamic_stack 0
		.amdhsa_enable_private_segment 0
		.amdhsa_system_sgpr_workgroup_id_x 1
		.amdhsa_system_sgpr_workgroup_id_y 0
		.amdhsa_system_sgpr_workgroup_id_z 0
		.amdhsa_system_sgpr_workgroup_info 0
		.amdhsa_system_vgpr_workitem_id 0
		.amdhsa_next_free_vgpr 256
		.amdhsa_next_free_sgpr 100
		.amdhsa_accum_offset 256
		.amdhsa_reserve_vcc 1
		.amdhsa_float_round_mode_32 0
		.amdhsa_float_round_mode_16_64 0
		.amdhsa_float_denorm_mode_32 3
		.amdhsa_float_denorm_mode_16_64 3
		.amdhsa_dx10_clamp 1
		.amdhsa_ieee_mode 1
		.amdhsa_fp16_overflow 0
		.amdhsa_tg_split 0
		.amdhsa_exception_fp_ieee_invalid_op 0
		.amdhsa_exception_fp_denorm_src 0
		.amdhsa_exception_fp_ieee_div_zero 0
		.amdhsa_exception_fp_ieee_overflow 0
		.amdhsa_exception_fp_ieee_underflow 0
		.amdhsa_exception_fp_ieee_inexact 0
		.amdhsa_exception_int_div_zero 0
	.end_amdhsa_kernel

amdhsa.kernels:
  - .agpr_count:     0
    .args:
      - .offset:         0
        .size:           224
        .value_kind:     by_value
      - .offset:         224
        .size:           4
        .value_kind:     hidden_block_count_x
      - .offset:         228
        .size:           4
        .value_kind:     hidden_block_count_y
      - .offset:         232
        .size:           4
        .value_kind:     hidden_block_count_z
      - .offset:         236
        .size:           2
        .value_kind:     hidden_group_size_x
      - .offset:         238
        .size:           2
        .value_kind:     hidden_group_size_y
      - .offset:         240
        .size:           2
        .value_kind:     hidden_group_size_z
      - .offset:         242
        .size:           2
        .value_kind:     hidden_remainder_x
      - .offset:         244
        .size:           2
        .value_kind:     hidden_remainder_y
      - .offset:         246
        .size:           2
        .value_kind:     hidden_remainder_z
      - .offset:         264
        .size:           8
        .value_kind:     hidden_global_offset_x
      - .offset:         272
        .size:           8
        .value_kind:     hidden_global_offset_y
      - .offset:         280
        .size:           8
        .value_kind:     hidden_global_offset_z
      - .offset:         288
        .size:           2
        .value_kind:     hidden_grid_dims
      - .offset:         344
        .size:           4
        .value_kind:     hidden_dynamic_lds_size
    .group_segment_fixed_size: 16
    .kernarg_segment_align: 8
    .kernarg_segment_size: 480
    .language:       OpenCL C
    .language_version:
      - 2
      - 0
    .max_flat_workgroup_size: 256
    .name:           _Z11mega_kernel1P
    .private_segment_fixed_size: 0
    .sgpr_count:     106
    .sgpr_spill_count: 71
    .symbol:         _Z11mega_kernel1P.kd
    .uniform_work_group_size: 1
    .uses_dynamic_stack: false
    .vgpr_count:     256
    .vgpr_spill_count: 0
    .wavefront_size: 64
